# grouped MLP2 walks the group's panels in reverse order (most recently written HID panels first: MALL hits)
# speedup vs baseline: 1.0723x; 1.0063x over previous
; #define PG8_WAIT_V(n) asm volatile("s_waitcnt vmcnt(" #n ")" ::: "memory")
; #define PG8_BAR __builtin_amdgcn_s_barrier()
; template <class Epi, class Sched>
; __device__ __forceinline__ void gemm_phase(LAS unsigned char* lds, const Gemm g, const Sched& S, const Epi& E) {
;     ...
;     const int wid = __builtin_amdgcn_readfirstlane(tid >> 6), lane = tid & 63, wr = wid >> 2, wc = wid & 3, fr = lane & 15, fq = lane >> 4;
;     int K = g.K; asm volatile("" : "+s"(K));
;     const int nt = K / BK;
;     unsigned voffA[2], voffB[2];
; #pragma unroll
;     for (int i = 0; i < 2; ++i) { int R, C; stage_rc(tid * 16 + i * 8192, R, C); const int Rb = Epi::PERM ? ((R & ~31) + perm32(R & 31)) : R;
;         voffA[i] = (unsigned)(R * K + C) * 2u; voffB[i] = (unsigned)(Rb * K + C) * 2u; }
;     const size_t kstep = (size_t)(BK * 2);
;     const size_t hstep = (size_t)HALF * K * 2;
;     const size_t tstep = 2 * hstep;
;     const unsigned ldsw = (unsigned)wid * 1024u;
;     const int aoff = lds_byte(wr * 64 + fr, fq * 8), boff = lds_byte(wc * 32 + fr, fq * 8);
;     ...
;     Unit cur, nxt; int ui = 0;
;     if (!S.next(0, cur)) return;
;     f32x4 acc[2][2][4][2];
; #pragma unroll
;     for (int a = 0; a < 2; ++a)
; #pragma unroll
;         for (int b = 0; b < 2; ++b)
; #pragma unroll
;             for (int m = 0; m < 4; ++m)
; #pragma unroll
;                 for (int n = 0; n < 2; ++n) acc[a][b][m][n] = (f32x4){0.f, 0.f, 0.f, 0.f};
;     bf16x8 At[4][2], B0[2][2], B1[2][2];
;     const char* cA = (const char*)g.A + (size_t)cur.pm * tstep; const char* cB = (const char*)g.Bt + (size_t)cur.pn * tstep;
;     S.a_ready(cur);
;     PG8_STAGE(PG8_SB(0, 0), cB, voffB); PG8_STAGE(PG8_SB(0, 1), cB + hstep, voffB); PG8_STAGE(PG8_SA(0, 0), cA, voffA); PG8_STAGE(PG8_SA(0, 1), cA + hstep, voffA);
;     if (wr == 1) PG8_BAR;
;     PG8_WAIT_V(2); PG8_BAR;
;     PG8_STAGE(PG8_SB(1, 0), cB + kstep, voffB); PG8_STAGE(PG8_SA(1, 0), cA + kstep, voffA); PG8_STAGE(PG8_SB(1, 1), cB + hstep + kstep, voffB);
;     PG8_WAIT_V(6); PG8_BAR;
; __global__ void __launch_bounds__(512, 2) fwd_megakernel(Args a) {
;     ...
;         {
;             PHASE_PTRS();
;             pg8::Gemm g{(const bf16_t*)(PB + P_HID), (const bf16_t*)(ws + WS_W2) + (size_t)l * DM * DFF, DFF}; pg8::PanelOrder S{DM / 256};
;             pg8::EpiRes E{HBp, DM, ALPHA};
;             pg8::gemm_phase(lds, g, S, E);
.Lgrp_bar1_done:
	s_barrier
	s_load_dwordx2 s[44:45], s[2:3], 0xf8
	s_movk_i32 s40, 0x1000
	v_lshlrev_b32_e32 v0, 4, v15
	v_add_u32_e32 v2, 0x2000, v0
	v_ashrrev_i32_e32 v3, 31, v2
	v_lshrrev_b32_e32 v3, 22, v3
	v_add_u32_e32 v3, v2, v3
	v_ashrrev_i32_e32 v3, 10, v3
	v_mul_i32_i24_e32 v4, 0x400, v3
	v_sub_u32_e32 v2, v2, v4
	v_lshrrev_b32_e32 v4, 4, v2
	s_waitcnt lgkmcnt(0)
	s_add_u32 s1, s44, s88
	v_bitop3_b32 v2, v4, v2, 32 bitop3:0x6c
	s_addc_u32 s3, s45, s89
	v_ashrrev_i32_e32 v4, 31, v2
	s_add_u32 s2, s1, 0xe000000
	v_lshrrev_b32_e32 v4, 26, v4
	s_addc_u32 s3, s3, 0
	s_and_b32 s98, s88, 0x3000000
	s_sub_u32 s99, 0x3000000, s98
	s_add_u32 s2, s2, s99
	s_addc_u32 s3, s3, 0
	v_add_u32_e32 v4, v2, v4
	v_lshlrev_b32_e32 v6, 3, v3
	s_add_u32 s1, s44, s10
	v_ashrrev_i32_e32 v5, 6, v4
	v_and_b32_e32 v6, -16, v6
	v_lshlrev_b32_e32 v3, 5, v3
	s_addc_u32 s4, s45, s11
	v_add_u32_e32 v6, v5, v6
	v_and_b32_e32 v14, 32, v3
	v_and_b32_e32 v3, 0xc0, v4
	s_add_u32 s10, s1, 0x2000000
	v_and_b32_e32 v5, 3, v5
	s_mov_b32 s1, 0x7fffffe0
	v_lshrrev_b32_e32 v7, 2, v6
	v_lshlrev_b32_e32 v8, 1, v6
	v_sub_u32_e32 v2, v2, v3
	v_and_or_b32 v5, v6, s1, v5
	v_and_b32_e32 v7, 4, v7
	v_and_b32_e32 v8, 24, v8
	v_ashrrev_i16_sdwa v2, v227, sext(v2) dst_sel:DWORD dst_unused:UNUSED_PAD src0_sel:DWORD src1_sel:BYTE_0
	v_or3_b32 v5, v5, v7, v8
	v_bfe_i32 v16, v2, 0, 16
	v_add_u32_e32 v2, v14, v16
	v_mul_lo_u32 v5, v5, s40
	v_mul_lo_u32 v17, v6, s40
	v_add_lshl_u32 v142, v5, v2, 1
	v_add_lshl_u32 v144, v2, v17, 1
	v_bfe_i32 v2, v15, 27, 1
	v_lshrrev_b32_e32 v2, 22, v2
	v_add_u32_e32 v2, v0, v2
	v_and_b32_e32 v2, 0xfffffc00, v2
	v_sub_u32_e32 v0, v0, v2
	v_lshrrev_b32_e32 v2, 4, v0
	v_ashrrev_i32_e32 v4, 31, v15
	v_bitop3_b32 v0, v2, v0, 32 bitop3:0x6c
	v_lshrrev_b32_e32 v4, 26, v4
	v_ashrrev_i32_e32 v2, 31, v0
	v_add_u32_e32 v4, v15, v4
	v_lshrrev_b32_e32 v2, 26, v2
	v_ashrrev_i32_e32 v4, 6, v4
	v_add_u32_e32 v2, v0, v2
	v_lshlrev_b32_e32 v5, 3, v4
	v_ashrrev_i32_e32 v3, 6, v2
	v_and_b32_e32 v5, -16, v5
	v_add_u32_e32 v5, v3, v5
	v_and_b32_e32 v2, 0xc0, v2
	v_readfirstlane_b32 s8, v15
	v_and_b32_e32 v3, 3, v3
	v_lshrrev_b32_e32 v6, 2, v5
	v_lshlrev_b32_e32 v7, 1, v5
	v_sub_u32_e32 v0, v0, v2
	s_addc_u32 s11, s4, 0
	s_lshr_b32 s99, s98, 3
	s_add_u32 s10, s10, s99
	s_addc_u32 s11, s11, 0
	s_ashr_i32 s9, s8, 6
	v_and_or_b32 v3, v5, s1, v3
	v_and_b32_e32 v6, 4, v6
	v_and_b32_e32 v7, 24, v7
	v_lshlrev_b32_e32 v4, 5, v4
	v_ashrrev_i16_sdwa v0, v227, sext(v0) dst_sel:DWORD dst_unused:UNUSED_PAD src0_sel:DWORD src1_sel:BYTE_0
	s_lshl_b32 s4, s9, 10
	v_or3_b32 v3, v3, v6, v7
	v_and_b32_e32 v18, 32, v4
	v_bfe_i32 v19, v0, 0, 16
	v_mul_lo_u32 v3, v3, s40
	v_add_u32_e32 v2, v18, v19
	s_add_i32 s5, s4, 0
	s_ashr_i32 s41, s40, 31
	v_add_lshl_u32 v0, v3, v2, 1
	s_add_i32 m0, s5, 0x10000
	s_ashr_i32 s36, s8, 8
	s_lshl_b64 s[18:19], s[40:41], 8
	global_load_lds_dwordx4 v0, s[10:11]
	s_add_i32 m0, s5, 0x12000
	s_add_u32 s26, s10, s18
	global_load_lds_dwordx4 v142, s[10:11]
	s_addc_u32 s27, s11, s19
	s_add_i32 m0, s5, 0x14000
	v_mul_lo_u32 v20, v5, s40
	v_mov_b32_e32 v143, v1
	global_load_lds_dwordx4 v0, s[26:27]
	s_add_i32 m0, s5, 0x16000
	s_add_i32 s52, s5, 0x2000
	v_add_lshl_u32 v146, v2, v20, 1
	v_lshl_add_u64 v[6:7], s[26:27], 0, v[0:1]
	v_lshl_add_u64 v[8:9], s[26:27], 0, v[142:143]
	global_load_lds_dwordx4 v142, s[26:27]
	s_mov_b32 m0, s5
	s_add_u32 s26, s2, s18
	global_load_lds_dwordx4 v146, s[2:3]
	s_mov_b32 m0, s52
	s_addc_u32 s27, s3, s19
	s_add_i32 s53, s5, 0x4000
	global_load_lds_dwordx4 v144, s[2:3]
	s_mov_b32 m0, s53
	s_add_i32 s54, s5, 0x6000
	global_load_lds_dwordx4 v146, s[26:27]
	s_mov_b32 m0, s54
	v_mov_b32_e32 v147, v1
	global_load_lds_dwordx4 v144, s[26:27]
	v_mov_b32_e32 v145, v1
	s_cmp_eq_u32 s36, 1
	v_lshl_add_u64 v[2:3], s[10:11], 0, v[0:1]
	v_lshl_add_u64 v[4:5], s[10:11], 0, v[142:143]
	v_lshl_add_u64 v[10:11], s[2:3], 0, v[146:147]
	v_lshl_add_u64 v[12:13], s[2:3], 0, v[144:145]
	s_cselect_b64 s[26:27], -1, 0
	s_cmp_lg_u32 s36, 1
	s_cbranch_scc1 .LBB0_443
	s_barrier
.LBB0_443:
	v_readlane_b32 s38, v249, 8
	v_readlane_b32 s39, v249, 9
	s_add_u32 s46, s44, s38
	s_addc_u32 s47, s45, s39
	s_add_i32 m0, s5, 0x18000
	v_lshl_add_u64 v[2:3], v[2:3], 0, s[6:7]
	s_waitcnt vmcnt(2)
	s_barrier
	global_load_lds_dwordx4 v[2:3], off
	v_lshl_add_u64 v[2:3], v[4:5], 0, s[6:7]
	s_add_i32 m0, s5, 0x1a000
	s_add_i32 s55, s5, 0x8000
	global_load_lds_dwordx4 v[2:3], off
	v_lshl_add_u64 v[2:3], v[10:11], 0, s[6:7]
	s_mov_b32 m0, s55
	s_add_i32 s56, s5, 0xa000
	global_load_lds_dwordx4 v[2:3], off
	v_lshl_add_u64 v[2:3], v[12:13], 0, s[6:7]
	s_mov_b32 m0, s56
	s_lshr_b32 s1, s41, 26
	global_load_lds_dwordx4 v[2:3], off
	s_add_i32 m0, s5, 0x1c000
	v_lshl_add_u64 v[2:3], v[6:7], 0, s[6:7]
	global_load_lds_dwordx4 v[2:3], off
	v_lshl_add_u64 v[2:3], v[8:9], 0, s[6:7]
	s_add_i32 m0, s5, 0x1e000
	s_add_i32 s1, s40, s1
	global_load_lds_dwordx4 v[2:3], off
	v_and_b32_e32 v3, 15, v15
	v_and_b32_e32 v4, 48, v15
	v_lshlrev_b32_e32 v5, 2, v15
	s_ashr_i32 s57, s1, 6
	v_lshl_or_b32 v2, s36, 6, v3
	v_lshl_or_b32 v3, v3, 6, v4
	s_lshl_b32 s1, s36, 13
	v_and_b32_e32 v5, 32, v5
	v_bitop3_b32 v6, v3, s1, v5 bitop3:0xde
	s_lshl_b32 s1, s9, 5
	s_and_b32 s1, s1, 0x60
	s_lshl_b64 s[38:39], s[40:41], 9
	s_lshl_b32 s9, s1, 7
	s_cmp_gt_i32 s40, 63
	v_bitop3_b32 v160, v3, s9, v5 bitop3:0xde
	s_cselect_b64 s[40:41], -1, 0
	s_add_i32 s58, s57, -2
	v_ashrrev_i32_e32 v3, 31, v2
	s_cmpk_lt_u32 s8, 0x100
	v_lshlrev_b64 v[2:3], 11, v[2:3]
	s_cselect_b64 s[42:43], -1, 0
	v_lshl_add_u64 v[2:3], s[46:47], 0, v[2:3]
	s_lshl_b32 s36, s1, 1
	v_lshl_add_u64 v[2:3], v[2:3], 0, s[36:37]
	v_mov_b32_e32 v5, v1
	v_lshl_add_u64 v[2:3], v[2:3], 0, v[4:5]
	s_mov_b64 s[8:9], 0x6000000
	v_readlane_b32 s1, v248, 24
	v_lshl_add_u64 v[148:149], v[2:3], 0, s[8:9]
	s_lshr_b32 s100, s98, 15
	s_lshr_b32 s99, s98, 2
	s_sub_u32 s100, s100, s99
	s_subb_u32 s101, 0, 0
	v_lshl_add_u64 v[148:149], v[148:149], 0, s[100:101]
	s_add_u32 s1, s44, s1
	v_readlane_b32 s8, v248, 25
	s_addc_u32 s9, s45, s8
	v_add_u32_e32 v2, v20, v18
	s_add_u32 s8, s1, s18
	v_add_lshl_u32 v2, v2, v19, 1
	v_mov_b32_e32 v3, v1
	s_addc_u32 s9, s9, s19
	s_sub_u32 s99, 0x3000000, s98
	s_add_u32 s8, s8, s99
	s_addc_u32 s9, s9, 0
	s_waitcnt vmcnt(6)
	v_lshl_add_u64 v[150:151], s[8:9], 0, v[2:3]
	v_add_u32_e32 v2, v17, v14
	v_add_lshl_u32 v2, v2, v16, 1
	v_lshl_add_u64 v[152:153], s[8:9], 0, v[2:3]
	s_mov_b32 s8, 0
	v_add_u32_e32 v161, 0, v6
	s_mov_b64 s[46:47], s[10:11]
	s_mov_b64 s[44:45], s[10:11]
	s_barrier
	s_branch .LBB0_446

; template <class Epi, class Sched>
; __device__ __forceinline__ void gemm_phase(LAS unsigned char* lds, const Gemm g, const Sched& S, const Epi& E) {
;     ...
;     for (;;) {
;         const bool has_next = S.next(ui + 1, nxt);
;         const char* nA = has_next ? (const char*)g.A + (size_t)nxt.pm * tstep : cA; const char* nB = has_next ? (const char*)g.Bt + (size_t)nxt.pn * tstep : cB;
;         for (int t = 0; t < nt; t += 2) {
;             const bool last = (t == nt - 2);
;             const char* a1 = cA + (size_t)(t + 1) * kstep;
;             const char* a2 = last ? nA : cA + (size_t)(t + 2) * kstep; const char* b2 = last ? nB : cB + (size_t)(t + 2) * kstep;
;             const char* a3 = a2 + kstep; const char* b3 = b2 + kstep;
;             if (last && has_next) S.a_ready(nxt);
;     ...
;         cur = nxt; cA = nA; cB = nB; ++ui;
.LBB0_445:
	s_andn2_b64 vcc, exec, s[8:9]
	s_sub_u32 s2, s2, 0x1000000
	s_subb_u32 s3, s3, 0
	s_mov_b32 s100, 0xff000000
	s_mov_b32 s101, -1
	v_lshl_add_u64 v[150:151], v[150:151], 0, s[100:101]
	v_lshl_add_u64 v[152:153], v[152:153], 0, s[100:101]
	s_mov_b32 s8, s59
	s_mov_b64 s[46:47], s[44:45]
	s_cbranch_vccz .LBB0_456

; #define PG8_STAGE(bufoff, gbase, voff) do { _Pragma("unroll") for (int _i = 0; _i < 2; ++_i) \
;         __builtin_amdgcn_global_load_lds((const unsigned*)((const char*)(gbase) + (voff)[_i]), (LAS unsigned*)(lds + (bufoff) + ldsw + _i * 8192), 16, 0, 0); } while (0)
; #define PG8_LDA(dst, b, h) do { _Pragma("unroll") for (int m = 0; m < 4; ++m) _Pragma("unroll") for (int k = 0; k < 2; ++k) dst[m][k] = *(const LAS bf16x8*)(lds + PG8_SA(b, h) + aoff + m * 2048 + k * 1024); } while (0)
; #define PG8_LDB(dst, b, h) do { _Pragma("unroll") for (int n = 0; n < 2; ++n) _Pragma("unroll") for (int k = 0; k < 2; ++k) dst[n][k] = *(const LAS bf16x8*)(lds + PG8_SB(b, h) + boff + n * 2048 + k * 1024); } while (0)
; #define PG8_MMA(ai, bj, At, Bt) do { __builtin_amdgcn_s_setprio(1); _Pragma("unroll") for (int m = 0; m < 4; ++m) _Pragma("unroll") for (int n = 0; n < 2; ++n) _Pragma("unroll") for (int k = 0; k < 2; ++k) \
;         acc[ai][bj][m][n] = __builtin_amdgcn_mfma_f32_16x16x32_bf16(Bt[n][k], At[m][k], acc[ai][bj][m][n], 0, 0, 0); __builtin_amdgcn_s_setprio(0); } while (0)
; #define PG8_WAIT_V(n) asm volatile("s_waitcnt vmcnt(" #n ")" ::: "memory")
; #define PG8_WAIT_L(n) asm volatile("s_waitcnt lgkmcnt(" #n ")" ::: "memory")
; #define PG8_BAR __builtin_amdgcn_s_barrier()
; template <class Epi, class Sched>
; __device__ __forceinline__ void gemm_phase(LAS unsigned char* lds, const Gemm g, const Sched& S, const Epi& E) {
;     ...
;         for (int t = 0; t < nt; t += 2) {
;             const bool last = (t == nt - 2);
;             const char* a1 = cA + (size_t)(t + 1) * kstep;
;             const char* a2 = last ? nA : cA + (size_t)(t + 2) * kstep; const char* b2 = last ? nB : cB + (size_t)(t + 2) * kstep;
;             const char* a3 = a2 + kstep; const char* b3 = b2 + kstep;
;             if (last && has_next) S.a_ready(nxt);
;             PG8_LDB(B0, 0, 0); PG8_LDB(B1, 0, 1); PG8_SCHED; PG8_LDA(At, 0, 0); PG8_STAGE(PG8_SA(1, 1), a1 + hstep, voffA);
;             PG8_WAIT_V(8); PG8_WAIT_L(0); PG8_BAR; PG8_MMA(0, 0, At, B0); PG8_MMA(0, 1, At, B1); PG8_BAR; PG8_SCHED;
;             PG8_LDA(At, 0, 1); PG8_STAGE(PG8_SB(0, 0), b2, voffB); PG8_STAGE(PG8_SB(0, 1), b2 + hstep, voffB); PG8_STAGE(PG8_SA(0, 0), a2, voffA);
;             PG8_WAIT_V(8); PG8_WAIT_L(0); PG8_BAR; PG8_MMA(1, 0, At, B0); PG8_MMA(1, 1, At, B1); PG8_BAR; PG8_SCHED;
.LBB0_450:
	s_add_i32 s60, s50, 2
	s_add_u32 s48, s46, 0x100
	s_addc_u32 s49, s47, 0
	s_add_u32 s1, s9, s46
	s_addc_u32 s51, s36, s47
	s_cmp_eq_u32 s58, s50
	s_cselect_b32 s50, 0xff000000, s48
	s_cselect_b32 s61, -1, s49
	s_cselect_b32 s62, s44, s1
	s_cselect_b32 s63, s45, s51
	s_add_u32 s50, s2, s50
	s_addc_u32 s51, s3, s61
	s_add_i32 s1, 0, 0x10000
	s_add_i32 s61, 0, 0x14000
	v_add_u32_e32 v154, s1, v160
	v_add_u32_e32 v158, s61, v160
	ds_read_b128 v[130:133], v154
	ds_read_b128 v[134:137], v154 offset:1024
	ds_read_b128 v[138:141], v154 offset:2048
	ds_read_b128 v[154:157], v154 offset:3072
	ds_read_b128 v[162:165], v158
	ds_read_b128 v[166:169], v158 offset:1024
	ds_read_b128 v[170:173], v158 offset:2048
	ds_read_b128 v[174:177], v158 offset:3072
	v_lshl_add_u64 v[158:159], v[150:151], 0, s[46:47]
	s_add_i32 m0, s5, 0xc000
	ds_read_b128 v[178:181], v161
	ds_read_b128 v[182:185], v161 offset:1024
	ds_read_b128 v[192:195], v161 offset:2048
	ds_read_b128 v[196:199], v161 offset:3072
	ds_read_b128 v[200:203], v161 offset:4096
	ds_read_b128 v[204:207], v161 offset:5120
	ds_read_b128 v[208:211], v161 offset:6144
	ds_read_b128 v[212:215], v161 offset:7168
	global_load_lds_dwordx4 v[158:159], off
	v_lshl_add_u64 v[158:159], v[152:153], 0, s[46:47]
	s_add_i32 m0, s5, 0xe000
	s_nop 0
	global_load_lds_dwordx4 v[158:159], off
	s_waitcnt vmcnt(8)
	s_waitcnt lgkmcnt(0)
	s_barrier
	s_setprio 1
	s_waitcnt lgkmcnt(0)
	v_mfma_f32_16x16x32_bf16 v[122:125], v[130:133], v[178:181], v[122:125]
	v_mfma_f32_16x16x32_bf16 v[126:129], v[138:141], v[178:181], v[126:129]
	v_mfma_f32_16x16x32_bf16 v[110:113], v[130:133], v[192:195], v[110:113]
	v_mfma_f32_16x16x32_bf16 v[106:109], v[138:141], v[192:195], v[106:109]
	v_mfma_f32_16x16x32_bf16 v[94:97], v[130:133], v[200:203], v[94:97]
	v_mfma_f32_16x16x32_bf16 v[90:93], v[138:141], v[200:203], v[90:93]
	v_mfma_f32_16x16x32_bf16 v[78:81], v[130:133], v[208:211], v[78:81]
	v_mfma_f32_16x16x32_bf16 v[74:77], v[138:141], v[208:211], v[74:77]
	v_mfma_f32_16x16x32_bf16 v[122:125], v[134:137], v[182:185], v[122:125]
	v_mfma_f32_16x16x32_bf16 v[126:129], v[154:157], v[182:185], v[126:129]
	v_mfma_f32_16x16x32_bf16 v[110:113], v[134:137], v[196:199], v[110:113]
	v_mfma_f32_16x16x32_bf16 v[106:109], v[154:157], v[196:199], v[106:109]
	v_mfma_f32_16x16x32_bf16 v[94:97], v[134:137], v[204:207], v[94:97]
	v_mfma_f32_16x16x32_bf16 v[90:93], v[154:157], v[204:207], v[90:93]
	v_mfma_f32_16x16x32_bf16 v[78:81], v[134:137], v[212:215], v[78:81]
	v_mfma_f32_16x16x32_bf16 v[74:77], v[154:157], v[212:215], v[74:77]
	s_setprio 0
	s_setprio 1
	v_mfma_f32_16x16x32_bf16 v[118:121], v[162:165], v[178:181], v[118:121]
	v_mfma_f32_16x16x32_bf16 v[114:117], v[170:173], v[178:181], v[114:117]
	v_mfma_f32_16x16x32_bf16 v[102:105], v[162:165], v[192:195], v[102:105]
	v_mfma_f32_16x16x32_bf16 v[98:101], v[170:173], v[192:195], v[98:101]
	v_mfma_f32_16x16x32_bf16 v[86:89], v[162:165], v[200:203], v[86:89]
	v_mfma_f32_16x16x32_bf16 v[82:85], v[170:173], v[200:203], v[82:85]
	v_mfma_f32_16x16x32_bf16 v[70:73], v[162:165], v[208:211], v[70:73]
	v_mfma_f32_16x16x32_bf16 v[66:69], v[170:173], v[208:211], v[66:69]
	v_mfma_f32_16x16x32_bf16 v[118:121], v[166:169], v[182:185], v[118:121]
	v_mfma_f32_16x16x32_bf16 v[114:117], v[174:177], v[182:185], v[114:117]
	v_mfma_f32_16x16x32_bf16 v[102:105], v[166:169], v[196:199], v[102:105]
	v_mfma_f32_16x16x32_bf16 v[98:101], v[174:177], v[196:199], v[98:101]
	v_mfma_f32_16x16x32_bf16 v[86:89], v[166:169], v[204:207], v[86:89]
	v_mfma_f32_16x16x32_bf16 v[82:85], v[174:177], v[204:207], v[82:85]
	v_mfma_f32_16x16x32_bf16 v[70:73], v[166:169], v[212:215], v[70:73]
	v_mfma_f32_16x16x32_bf16 v[66:69], v[174:177], v[212:215], v[66:69]
	s_setprio 0
	s_barrier
	s_add_i32 s1, s1, s4
	v_lshl_add_u64 v[158:159], s[62:63], 0, v[0:1]
	s_mov_b32 m0, s1
	ds_read_b128 v[178:181], v161 offset:16384
	ds_read_b128 v[182:185], v161 offset:17408
	ds_read_b128 v[192:195], v161 offset:18432
	ds_read_b128 v[196:199], v161 offset:19456
	ds_read_b128 v[200:203], v161 offset:20480
	ds_read_b128 v[204:207], v161 offset:21504
	ds_read_b128 v[208:211], v161 offset:22528
	ds_read_b128 v[212:215], v161 offset:23552
	global_load_lds_dwordx4 v[158:159], off
	s_add_i32 m0, s1, 0x2000
	s_add_u32 s46, s62, s18
	v_lshl_add_u64 v[186:187], s[62:63], 0, v[142:143]
	s_addc_u32 s47, s63, s19
	s_add_i32 s1, s61, s4
	global_load_lds_dwordx4 v[186:187], off
	v_lshl_add_u64 v[216:217], s[46:47], 0, v[0:1]
	s_mov_b32 m0, s1
	v_lshl_add_u64 v[238:239], s[46:47], 0, v[142:143]
	global_load_lds_dwordx4 v[216:217], off
	s_add_i32 m0, s1, 0x2000
	v_lshl_add_u64 v[240:241], s[50:51], 0, v[146:147]
	global_load_lds_dwordx4 v[238:239], off
	s_mov_b32 m0, s5
	v_lshl_add_u64 v[244:245], s[50:51], 0, v[144:145]
	global_load_lds_dwordx4 v[240:241], off
	s_mov_b32 m0, s52
	s_nop 0
	global_load_lds_dwordx4 v[244:245], off
	s_waitcnt vmcnt(8)
	s_waitcnt lgkmcnt(0)
	s_barrier
; #define PG8_STAGE(bufoff, gbase, voff) do { _Pragma("unroll") for (int _i = 0; _i < 2; ++_i) \
;         __builtin_amdgcn_global_load_lds((const unsigned*)((const char*)(gbase) + (voff)[_i]), (LAS unsigned*)(lds + (bufoff) + ldsw + _i * 8192), 16, 0, 0); } while (0)
; #define PG8_LDA(dst, b, h) do { _Pragma("unroll") for (int m = 0; m < 4; ++m) _Pragma("unroll") for (int k = 0; k < 2; ++k) dst[m][k] = *(const LAS bf16x8*)(lds + PG8_SA(b, h) + aoff + m * 2048 + k * 1024); } while (0)
; #define PG8_LDB(dst, b, h) do { _Pragma("unroll") for (int n = 0; n < 2; ++n) _Pragma("unroll") for (int k = 0; k < 2; ++k) dst[n][k] = *(const LAS bf16x8*)(lds + PG8_SB(b, h) + boff + n * 2048 + k * 1024); } while (0)
; #define PG8_MMA(ai, bj, At, Bt) do { __builtin_amdgcn_s_setprio(1); _Pragma("unroll") for (int m = 0; m < 4; ++m) _Pragma("unroll") for (int n = 0; n < 2; ++n) _Pragma("unroll") for (int k = 0; k < 2; ++k) \
;         acc[ai][bj][m][n] = __builtin_amdgcn_mfma_f32_16x16x32_bf16(Bt[n][k], At[m][k], acc[ai][bj][m][n], 0, 0, 0); __builtin_amdgcn_s_setprio(0); } while (0)
; #define PG8_WAIT_V(n) asm volatile("s_waitcnt vmcnt(" #n ")" ::: "memory")
; #define PG8_WAIT_L(n) asm volatile("s_waitcnt lgkmcnt(" #n ")" ::: "memory")
; #define PG8_BAR __builtin_amdgcn_s_barrier()
; #define PG8_SCHED __builtin_amdgcn_sched_barrier(0)
; template <class Epi, class Sched>
; __device__ __forceinline__ void gemm_phase(LAS unsigned char* lds, const Gemm g, const Sched& S, const Epi& E) {
;     ...
;             PG8_WAIT_V(8); PG8_WAIT_L(0); PG8_BAR; PG8_MMA(1, 0, At, B0); PG8_MMA(1, 1, At, B1); PG8_BAR; PG8_SCHED;
;             PG8_LDB(B0, 1, 0); PG8_LDB(B1, 1, 1); PG8_SCHED; PG8_LDA(At, 1, 0); PG8_STAGE(PG8_SA(0, 1), a2 + hstep, voffA);
;             PG8_WAIT_V(8); PG8_WAIT_L(0); PG8_BAR; PG8_MMA(0, 0, At, B0); PG8_MMA(0, 1, At, B1); PG8_BAR; PG8_SCHED;
	s_setprio 1
	s_waitcnt lgkmcnt(0)
	v_mfma_f32_16x16x32_bf16 v[62:65], v[130:133], v[178:181], v[62:65]
	v_mfma_f32_16x16x32_bf16 v[58:61], v[138:141], v[178:181], v[58:61]
	v_mfma_f32_16x16x32_bf16 v[46:49], v[130:133], v[192:195], v[46:49]
	v_mfma_f32_16x16x32_bf16 v[42:45], v[138:141], v[192:195], v[42:45]
	v_mfma_f32_16x16x32_bf16 v[30:33], v[130:133], v[200:203], v[30:33]
	v_mfma_f32_16x16x32_bf16 v[26:29], v[138:141], v[200:203], v[26:29]
	v_mfma_f32_16x16x32_bf16 v[14:17], v[130:133], v[208:211], v[14:17]
	v_mfma_f32_16x16x32_bf16 v[10:13], v[138:141], v[208:211], v[10:13]
	v_mfma_f32_16x16x32_bf16 v[62:65], v[134:137], v[182:185], v[62:65]
	v_mfma_f32_16x16x32_bf16 v[58:61], v[154:157], v[182:185], v[58:61]
	v_mfma_f32_16x16x32_bf16 v[46:49], v[134:137], v[196:199], v[46:49]
	v_mfma_f32_16x16x32_bf16 v[42:45], v[154:157], v[196:199], v[42:45]
	v_mfma_f32_16x16x32_bf16 v[30:33], v[134:137], v[204:207], v[30:33]
	v_mfma_f32_16x16x32_bf16 v[26:29], v[154:157], v[204:207], v[26:29]
	v_mfma_f32_16x16x32_bf16 v[14:17], v[134:137], v[212:215], v[14:17]
	v_mfma_f32_16x16x32_bf16 v[10:13], v[154:157], v[212:215], v[10:13]
	s_setprio 0
	s_setprio 1
	v_mfma_f32_16x16x32_bf16 v[54:57], v[162:165], v[178:181], v[54:57]
	v_mfma_f32_16x16x32_bf16 v[50:53], v[170:173], v[178:181], v[50:53]
	v_mfma_f32_16x16x32_bf16 v[38:41], v[162:165], v[192:195], v[38:41]
	v_mfma_f32_16x16x32_bf16 v[34:37], v[170:173], v[192:195], v[34:37]
	v_mfma_f32_16x16x32_bf16 v[22:25], v[162:165], v[200:203], v[22:25]
	v_mfma_f32_16x16x32_bf16 v[18:21], v[170:173], v[200:203], v[18:21]
	v_mfma_f32_16x16x32_bf16 v[6:9], v[162:165], v[208:211], v[6:9]
	v_mfma_f32_16x16x32_bf16 v[2:5], v[170:173], v[208:211], v[2:5]
	v_mfma_f32_16x16x32_bf16 v[54:57], v[166:169], v[182:185], v[54:57]
	v_mfma_f32_16x16x32_bf16 v[50:53], v[174:177], v[182:185], v[50:53]
	v_mfma_f32_16x16x32_bf16 v[38:41], v[166:169], v[196:199], v[38:41]
	v_mfma_f32_16x16x32_bf16 v[34:37], v[174:177], v[196:199], v[34:37]
	v_mfma_f32_16x16x32_bf16 v[22:25], v[166:169], v[204:207], v[22:25]
	v_mfma_f32_16x16x32_bf16 v[18:21], v[174:177], v[204:207], v[18:21]
	v_mfma_f32_16x16x32_bf16 v[6:9], v[166:169], v[212:215], v[6:9]
	v_mfma_f32_16x16x32_bf16 v[2:5], v[174:177], v[212:215], v[2:5]
	s_setprio 0
	s_barrier
	s_add_i32 s1, 0, 0x18000
	s_add_i32 s61, 0, 0x1c000
	v_add_u32_e32 v154, s1, v160
	v_add_u32_e32 v174, s61, v160
	ds_read_b128 v[130:133], v154
	ds_read_b128 v[134:137], v154 offset:1024
	ds_read_b128 v[138:141], v154 offset:2048
	ds_read_b128 v[154:157], v154 offset:3072
	ds_read_b128 v[162:165], v174
	ds_read_b128 v[166:169], v174 offset:1024
	ds_read_b128 v[170:173], v174 offset:2048
	ds_read_b128 v[174:177], v174 offset:3072
	s_add_u32 s46, s50, s18
	s_addc_u32 s47, s51, s19
	s_mov_b32 m0, s53
	v_lshl_add_u64 v[246:247], s[46:47], 0, v[146:147]
	ds_read_b128 v[178:181], v161 offset:32768
	ds_read_b128 v[182:185], v161 offset:33792
	ds_read_b128 v[192:195], v161 offset:34816
	ds_read_b128 v[196:199], v161 offset:35840
	ds_read_b128 v[200:203], v161 offset:36864
	ds_read_b128 v[204:207], v161 offset:37888
	ds_read_b128 v[208:211], v161 offset:38912
	ds_read_b128 v[212:215], v161 offset:39936
	global_load_lds_dwordx4 v[246:247], off
	v_lshl_add_u64 v[246:247], s[46:47], 0, v[144:145]
	s_mov_b32 m0, s54
	s_nop 0
	global_load_lds_dwordx4 v[246:247], off
	s_waitcnt vmcnt(8)
	s_waitcnt lgkmcnt(0)
	s_barrier
	s_setprio 1
	s_waitcnt lgkmcnt(0)
	v_mfma_f32_16x16x32_bf16 v[122:125], v[130:133], v[178:181], v[122:125]
	v_mfma_f32_16x16x32_bf16 v[126:129], v[138:141], v[178:181], v[126:129]
	v_mfma_f32_16x16x32_bf16 v[110:113], v[130:133], v[192:195], v[110:113]
	v_mfma_f32_16x16x32_bf16 v[106:109], v[138:141], v[192:195], v[106:109]
	v_mfma_f32_16x16x32_bf16 v[94:97], v[130:133], v[200:203], v[94:97]
	v_mfma_f32_16x16x32_bf16 v[90:93], v[138:141], v[200:203], v[90:93]
	v_mfma_f32_16x16x32_bf16 v[78:81], v[130:133], v[208:211], v[78:81]
	v_mfma_f32_16x16x32_bf16 v[74:77], v[138:141], v[208:211], v[74:77]
	v_mfma_f32_16x16x32_bf16 v[122:125], v[134:137], v[182:185], v[122:125]
	v_mfma_f32_16x16x32_bf16 v[126:129], v[154:157], v[182:185], v[126:129]
	v_mfma_f32_16x16x32_bf16 v[110:113], v[134:137], v[196:199], v[110:113]
	v_mfma_f32_16x16x32_bf16 v[106:109], v[154:157], v[196:199], v[106:109]
	v_mfma_f32_16x16x32_bf16 v[94:97], v[134:137], v[204:207], v[94:97]
	v_mfma_f32_16x16x32_bf16 v[90:93], v[154:157], v[204:207], v[90:93]
	v_mfma_f32_16x16x32_bf16 v[78:81], v[134:137], v[212:215], v[78:81]
	v_mfma_f32_16x16x32_bf16 v[74:77], v[154:157], v[212:215], v[74:77]
	s_setprio 0
	s_setprio 1
	v_mfma_f32_16x16x32_bf16 v[118:121], v[162:165], v[178:181], v[118:121]
	v_mfma_f32_16x16x32_bf16 v[114:117], v[170:173], v[178:181], v[114:117]
	v_mfma_f32_16x16x32_bf16 v[102:105], v[162:165], v[192:195], v[102:105]
	v_mfma_f32_16x16x32_bf16 v[98:101], v[170:173], v[192:195], v[98:101]
	v_mfma_f32_16x16x32_bf16 v[86:89], v[162:165], v[200:203], v[86:89]
	v_mfma_f32_16x16x32_bf16 v[82:85], v[170:173], v[200:203], v[82:85]
	v_mfma_f32_16x16x32_bf16 v[70:73], v[162:165], v[208:211], v[70:73]
	v_mfma_f32_16x16x32_bf16 v[66:69], v[170:173], v[208:211], v[66:69]
	v_mfma_f32_16x16x32_bf16 v[118:121], v[166:169], v[182:185], v[118:121]
	v_mfma_f32_16x16x32_bf16 v[114:117], v[174:177], v[182:185], v[114:117]
	v_mfma_f32_16x16x32_bf16 v[102:105], v[166:169], v[196:199], v[102:105]
	v_mfma_f32_16x16x32_bf16 v[98:101], v[174:177], v[196:199], v[98:101]
	v_mfma_f32_16x16x32_bf16 v[86:89], v[166:169], v[204:207], v[86:89]
	v_mfma_f32_16x16x32_bf16 v[82:85], v[174:177], v[204:207], v[82:85]
	v_mfma_f32_16x16x32_bf16 v[70:73], v[166:169], v[212:215], v[70:73]
	v_mfma_f32_16x16x32_bf16 v[66:69], v[174:177], v[212:215], v[66:69]
	s_setprio 0
	s_barrier
; #define PG8_STAGE(bufoff, gbase, voff) do { _Pragma("unroll") for (int _i = 0; _i < 2; ++_i) \
;         __builtin_amdgcn_global_load_lds((const unsigned*)((const char*)(gbase) + (voff)[_i]), (LAS unsigned*)(lds + (bufoff) + ldsw + _i * 8192), 16, 0, 0); } while (0)
; #define PG8_LDA(dst, b, h) do { _Pragma("unroll") for (int m = 0; m < 4; ++m) _Pragma("unroll") for (int k = 0; k < 2; ++k) dst[m][k] = *(const LAS bf16x8*)(lds + PG8_SA(b, h) + aoff + m * 2048 + k * 1024); } while (0)
; #define PG8_MMA(ai, bj, At, Bt) do { __builtin_amdgcn_s_setprio(1); _Pragma("unroll") for (int m = 0; m < 4; ++m) _Pragma("unroll") for (int n = 0; n < 2; ++n) _Pragma("unroll") for (int k = 0; k < 2; ++k) \
;         acc[ai][bj][m][n] = __builtin_amdgcn_mfma_f32_16x16x32_bf16(Bt[n][k], At[m][k], acc[ai][bj][m][n], 0, 0, 0); __builtin_amdgcn_s_setprio(0); } while (0)
; #define PG8_WAIT_V(n) asm volatile("s_waitcnt vmcnt(" #n ")" ::: "memory")
; #define PG8_WAIT_L(n) asm volatile("s_waitcnt lgkmcnt(" #n ")" ::: "memory")
; #define PG8_BAR __builtin_amdgcn_s_barrier()
; #define PG8_SCHED __builtin_amdgcn_sched_barrier(0)
; template <class Epi, class Sched>
; __device__ __forceinline__ void gemm_phase(LAS unsigned char* lds, const Gemm g, const Sched& S, const Epi& E) {
;     ...
;             PG8_LDA(At, 1, 1); PG8_STAGE(PG8_SB(1, 0), b3, voffB); PG8_STAGE(PG8_SB(1, 1), b3 + hstep, voffB); PG8_STAGE(PG8_SA(1, 0), a3, voffA);
;             PG8_WAIT_V(8); PG8_WAIT_L(0); PG8_BAR; PG8_MMA(1, 0, At, B0); PG8_MMA(1, 1, At, B1); PG8_BAR; PG8_SCHED;
;         }
	s_add_i32 s1, s1, s4
	v_lshl_add_u64 v[158:159], v[158:159], 0, s[6:7]
	s_mov_b32 m0, s1
	ds_read_b128 v[178:181], v161 offset:49152
	ds_read_b128 v[182:185], v161 offset:50176
	ds_read_b128 v[192:195], v161 offset:51200
	ds_read_b128 v[196:199], v161 offset:52224
	ds_read_b128 v[200:203], v161 offset:53248
	ds_read_b128 v[204:207], v161 offset:54272
	ds_read_b128 v[208:211], v161 offset:55296
	ds_read_b128 v[212:215], v161 offset:56320
	global_load_lds_dwordx4 v[158:159], off
	v_lshl_add_u64 v[158:159], v[186:187], 0, s[6:7]
	s_add_i32 m0, s1, 0x2000
	s_add_i32 s1, s61, s4
	global_load_lds_dwordx4 v[158:159], off
	v_lshl_add_u64 v[158:159], v[216:217], 0, s[6:7]
	s_mov_b32 m0, s1
	s_nop 0
	global_load_lds_dwordx4 v[158:159], off
	v_lshl_add_u64 v[158:159], v[238:239], 0, s[6:7]
	s_add_i32 m0, s1, 0x2000
	s_nop 0
	global_load_lds_dwordx4 v[158:159], off
	v_lshl_add_u64 v[158:159], v[240:241], 0, s[6:7]
	s_mov_b32 m0, s55
	s_nop 0
	global_load_lds_dwordx4 v[158:159], off
	v_lshl_add_u64 v[158:159], v[244:245], 0, s[6:7]
	s_mov_b32 m0, s56
	s_nop 0
	global_load_lds_dwordx4 v[158:159], off
	s_waitcnt vmcnt(8)
	s_waitcnt lgkmcnt(0)
	s_barrier
	s_setprio 1
	s_waitcnt lgkmcnt(0)
	v_mfma_f32_16x16x32_bf16 v[62:65], v[130:133], v[178:181], v[62:65]
	v_mfma_f32_16x16x32_bf16 v[58:61], v[138:141], v[178:181], v[58:61]
	v_mfma_f32_16x16x32_bf16 v[46:49], v[130:133], v[192:195], v[46:49]
	v_mfma_f32_16x16x32_bf16 v[42:45], v[138:141], v[192:195], v[42:45]
	v_mfma_f32_16x16x32_bf16 v[30:33], v[130:133], v[200:203], v[30:33]
	v_mfma_f32_16x16x32_bf16 v[26:29], v[138:141], v[200:203], v[26:29]
	v_mfma_f32_16x16x32_bf16 v[14:17], v[130:133], v[208:211], v[14:17]
	v_mfma_f32_16x16x32_bf16 v[10:13], v[138:141], v[208:211], v[10:13]
	v_mfma_f32_16x16x32_bf16 v[62:65], v[134:137], v[182:185], v[62:65]
	v_mfma_f32_16x16x32_bf16 v[58:61], v[154:157], v[182:185], v[58:61]
	v_mfma_f32_16x16x32_bf16 v[46:49], v[134:137], v[196:199], v[46:49]
	v_mfma_f32_16x16x32_bf16 v[42:45], v[154:157], v[196:199], v[42:45]
	v_mfma_f32_16x16x32_bf16 v[30:33], v[134:137], v[204:207], v[30:33]
	v_mfma_f32_16x16x32_bf16 v[26:29], v[154:157], v[204:207], v[26:29]
	v_mfma_f32_16x16x32_bf16 v[14:17], v[134:137], v[212:215], v[14:17]
	v_mfma_f32_16x16x32_bf16 v[10:13], v[154:157], v[212:215], v[10:13]
	s_setprio 0
	s_setprio 1
	v_mfma_f32_16x16x32_bf16 v[54:57], v[162:165], v[178:181], v[54:57]
	v_mfma_f32_16x16x32_bf16 v[50:53], v[170:173], v[178:181], v[50:53]
	v_mfma_f32_16x16x32_bf16 v[38:41], v[162:165], v[192:195], v[38:41]
	v_mfma_f32_16x16x32_bf16 v[34:37], v[170:173], v[192:195], v[34:37]
	v_mfma_f32_16x16x32_bf16 v[22:25], v[162:165], v[200:203], v[22:25]
	v_mfma_f32_16x16x32_bf16 v[18:21], v[170:173], v[200:203], v[18:21]
	v_mfma_f32_16x16x32_bf16 v[6:9], v[162:165], v[208:211], v[6:9]
	v_mfma_f32_16x16x32_bf16 v[2:5], v[170:173], v[208:211], v[2:5]
	v_mfma_f32_16x16x32_bf16 v[54:57], v[166:169], v[182:185], v[54:57]
	v_mfma_f32_16x16x32_bf16 v[50:53], v[174:177], v[182:185], v[50:53]
	v_mfma_f32_16x16x32_bf16 v[38:41], v[166:169], v[196:199], v[38:41]
	v_mfma_f32_16x16x32_bf16 v[34:37], v[174:177], v[196:199], v[34:37]
	v_mfma_f32_16x16x32_bf16 v[22:25], v[166:169], v[204:207], v[22:25]
	v_mfma_f32_16x16x32_bf16 v[18:21], v[174:177], v[204:207], v[18:21]
	v_mfma_f32_16x16x32_bf16 v[6:9], v[166:169], v[212:215], v[6:9]
	v_mfma_f32_16x16x32_bf16 v[2:5], v[174:177], v[212:215], v[2:5]
	s_setprio 0
	s_barrier
	s_cmp_ge_i32 s60, s57
	s_mov_b64 s[46:47], s[48:49]
	s_mov_b32 s50, s60
	s_cbranch_scc0 .LBB0_450

; __device__ __forceinline__ float bflo_(unsigned w) { return __uint_as_float(w << 16); }
; __device__ __forceinline__ float bfhi_(unsigned w) { return __uint_as_float(w & 0xffff0000u); }
; __device__ __forceinline__ unsigned cvt_pk_bf16(float lo, float hi) { unsigned r; asm volatile("v_cvt_pk_bf16_f32 %0, %1, %2" : "=v"(r) : "v"(lo), "v"(hi)); return r; }
; #define PG8_OPQ(p) asm volatile("" : "+v"(p))
;     __device__ __forceinline__ void operator()(const f32x4 (&acc)[2][2][4][2], const Unit& u, int wr, int wc, int fr, int fq) const {
;         char* p = (char*)(HB + (size_t)(wr * 64 + fr) * ldc + u.pn * BM + wc * 32 + 8 * fq);
;         const size_t step = (size_t)16 * ldc * 2;
; #pragma unroll
;         for (int ai = 0; ai < 2; ++ai) {
;             PG8_OPQ(p);
;             u32x4 h[4][2];
; #pragma unroll
;             for (int m = 0; m < 4; ++m)
; #pragma unroll
;                 for (int bj = 0; bj < 2; ++bj) h[m][bj] = *(const u32x4*)(p + m * step + bj * HALF * 2);
; #pragma unroll
;             for (int m = 0; m < 4; ++m)
; #pragma unroll
;                 for (int bj = 0; bj < 2; ++bj) { const f32x4 v0 = acc[ai][bj][m][0], v1 = acc[ai][bj][m][1]; const u32x4 hh = h[m][bj];
;                     u32x4 w;
;                     w.x = cvt_pk_bf16(bflo_(hh.x) * alpha + v0[0], bfhi_(hh.x) * alpha + v0[1]); w.y = cvt_pk_bf16(bflo_(hh.y) * alpha + v0[2], bfhi_(hh.y) * alpha + v0[3]);
;                     w.z = cvt_pk_bf16(bflo_(hh.z) * alpha + v1[0], bfhi_(hh.z) * alpha + v1[1]); w.w = cvt_pk_bf16(bflo_(hh.w) * alpha + v1[2], bfhi_(hh.w) * alpha + v1[3]);
;                     *(u32x4*)(p + m * step + bj * HALF * 2) = w; }
.LBB0_453:
	s_sub_u32 s36, 3, s8
	s_lshl_b32 s36, s36, 21
	v_lshl_add_u64 v[154:155], s[36:37], 1, v[148:149]
	flat_load_dwordx4 v[162:165], v[154:155]
	flat_load_dwordx4 v[166:169], v[154:155] offset:256
	v_add_co_u32_e32 v182, vcc, 0x8000, v154
	s_cmp_eq_u32 s8, 3
	s_nop 0
	v_addc_co_u32_e32 v183, vcc, 0, v155, vcc
	flat_load_dwordx4 v[170:173], v[182:183]
	flat_load_dwordx4 v[174:177], v[182:183] offset:256
	v_add_co_u32_e32 v158, vcc, 0x10000, v154
	s_mov_b64 s[8:9], -1
	s_nop 0
	v_addc_co_u32_e32 v159, vcc, 0, v155, vcc
	flat_load_dwordx4 v[178:181], v[158:159]
	flat_load_dwordx4 v[138:141], v[158:159] offset:256
	v_add_co_u32_e32 v156, vcc, 0x18000, v154
	s_waitcnt vmcnt(0) lgkmcnt(0)
	v_lshlrev_b32_e32 v184, 16, v162
	v_addc_co_u32_e32 v157, vcc, 0, v155, vcc
	flat_load_dwordx4 v[134:137], v[156:157]
	flat_load_dwordx4 v[130:133], v[156:157] offset:256
	v_and_b32_e32 v162, 0xffff0000, v162
	v_lshlrev_b32_e32 v185, 16, v163
	v_and_b32_e32 v163, 0xffff0000, v163
	v_lshlrev_b32_e32 v186, 16, v164
	v_and_b32_e32 v164, 0xffff0000, v164
	v_lshlrev_b32_e32 v187, 16, v165
	v_and_b32_e32 v165, 0xffff0000, v165
	v_fmac_f32_e32 v122, 0x3fb504f3, v184
	v_fmac_f32_e32 v123, 0x3fb504f3, v162
	v_fmac_f32_e32 v124, 0x3fb504f3, v185
	v_fmac_f32_e32 v125, 0x3fb504f3, v163
	v_fmac_f32_e32 v126, 0x3fb504f3, v186
	v_fmac_f32_e32 v127, 0x3fb504f3, v164
	v_fmac_f32_e32 v128, 0x3fb504f3, v187
	v_lshlrev_b32_e32 v188, 16, v166
	v_and_b32_e32 v166, 0xffff0000, v166
	v_lshlrev_b32_e32 v190, 16, v167
	v_and_b32_e32 v167, 0xffff0000, v167
	v_fmac_f32_e32 v129, 0x3fb504f3, v165
	v_cvt_pk_bf16_f32 v122, v122, v123
	v_cvt_pk_bf16_f32 v123, v124, v125
	v_cvt_pk_bf16_f32 v124, v126, v127
	v_cvt_pk_bf16_f32 v125, v128, v129
	v_lshlrev_b32_e32 v126, 16, v170
	v_and_b32_e32 v127, 0xffff0000, v170
	v_lshlrev_b32_e32 v128, 16, v171
	v_lshlrev_b32_e32 v162, 16, v172
	v_lshlrev_b32_e32 v192, 16, v168
	v_and_b32_e32 v168, 0xffff0000, v168
	v_lshlrev_b32_e32 v193, 16, v169
	v_and_b32_e32 v169, 0xffff0000, v169
	v_fmac_f32_e32 v118, 0x3fb504f3, v188
	v_fmac_f32_e32 v119, 0x3fb504f3, v166
	v_fmac_f32_e32 v120, 0x3fb504f3, v190
	v_fmac_f32_e32 v121, 0x3fb504f3, v167
	v_and_b32_e32 v129, 0xffff0000, v171
	v_and_b32_e32 v163, 0xffff0000, v172
	v_fmac_f32_e32 v110, 0x3fb504f3, v126
	v_fmac_f32_e32 v111, 0x3fb504f3, v127
	v_fmac_f32_e32 v112, 0x3fb504f3, v128
	v_fmac_f32_e32 v106, 0x3fb504f3, v162
	v_fmac_f32_e32 v114, 0x3fb504f3, v192
	v_fmac_f32_e32 v115, 0x3fb504f3, v168
	v_fmac_f32_e32 v116, 0x3fb504f3, v193
	v_fmac_f32_e32 v117, 0x3fb504f3, v169
	flat_store_dwordx4 v[154:155], v[122:125]
	v_cvt_pk_bf16_f32 v118, v118, v119
	v_cvt_pk_bf16_f32 v119, v120, v121
	v_cvt_pk_bf16_f32 v120, v114, v115
	v_cvt_pk_bf16_f32 v121, v116, v117
	v_fmac_f32_e32 v113, 0x3fb504f3, v129
	v_fmac_f32_e32 v107, 0x3fb504f3, v163
	flat_store_dwordx4 v[154:155], v[118:121] offset:256
	v_cvt_pk_bf16_f32 v110, v110, v111
	v_cvt_pk_bf16_f32 v111, v112, v113
	v_cvt_pk_bf16_f32 v112, v106, v107
	v_lshlrev_b32_e32 v106, 16, v174
	v_fmac_f32_e32 v102, 0x3fb504f3, v106
	v_and_b32_e32 v106, 0xffff0000, v174
	v_lshlrev_b32_e32 v164, 16, v173
	v_and_b32_e32 v165, 0xffff0000, v173
	v_fmac_f32_e32 v103, 0x3fb504f3, v106
	v_fmac_f32_e32 v108, 0x3fb504f3, v164
	v_fmac_f32_e32 v109, 0x3fb504f3, v165
	v_cvt_pk_bf16_f32 v113, v108, v109
	flat_store_dwordx4 v[182:183], v[110:113]
	v_cvt_pk_bf16_f32 v102, v102, v103
	v_lshlrev_b32_e32 v103, 16, v175
	v_fmac_f32_e32 v104, 0x3fb504f3, v103
	v_and_b32_e32 v103, 0xffff0000, v175
	v_fmac_f32_e32 v105, 0x3fb504f3, v103
	v_cvt_pk_bf16_f32 v103, v104, v105
	v_lshlrev_b32_e32 v104, 16, v176
	v_fmac_f32_e32 v98, 0x3fb504f3, v104
	v_and_b32_e32 v104, 0xffff0000, v176
	v_fmac_f32_e32 v99, 0x3fb504f3, v104
	v_cvt_pk_bf16_f32 v104, v98, v99
	v_lshlrev_b32_e32 v98, 16, v177
	v_fmac_f32_e32 v100, 0x3fb504f3, v98
	v_and_b32_e32 v98, 0xffff0000, v177
	v_fmac_f32_e32 v101, 0x3fb504f3, v98
	v_lshlrev_b32_e32 v98, 16, v178
	v_fmac_f32_e32 v94, 0x3fb504f3, v98
	v_and_b32_e32 v98, 0xffff0000, v178
	v_fmac_f32_e32 v95, 0x3fb504f3, v98
	v_cvt_pk_bf16_f32 v105, v100, v101
	flat_store_dwordx4 v[182:183], v[102:105] offset:256
	v_cvt_pk_bf16_f32 v94, v94, v95
	v_lshlrev_b32_e32 v95, 16, v179
	v_fmac_f32_e32 v96, 0x3fb504f3, v95
	v_and_b32_e32 v95, 0xffff0000, v179
	v_fmac_f32_e32 v97, 0x3fb504f3, v95
	v_cvt_pk_bf16_f32 v95, v96, v97
	v_lshlrev_b32_e32 v96, 16, v180
	v_fmac_f32_e32 v90, 0x3fb504f3, v96
	v_and_b32_e32 v96, 0xffff0000, v180
	v_fmac_f32_e32 v91, 0x3fb504f3, v96
	v_cvt_pk_bf16_f32 v96, v90, v91
	v_lshlrev_b32_e32 v90, 16, v181
	v_fmac_f32_e32 v92, 0x3fb504f3, v90
	v_and_b32_e32 v90, 0xffff0000, v181
	v_fmac_f32_e32 v93, 0x3fb504f3, v90
	v_lshlrev_b32_e32 v90, 16, v138
	v_fmac_f32_e32 v86, 0x3fb504f3, v90
	v_and_b32_e32 v90, 0xffff0000, v138
	v_fmac_f32_e32 v87, 0x3fb504f3, v90
	v_cvt_pk_bf16_f32 v97, v92, v93
	flat_store_dwordx4 v[158:159], v[94:97]
	v_cvt_pk_bf16_f32 v86, v86, v87
	v_lshlrev_b32_e32 v87, 16, v139
	v_fmac_f32_e32 v88, 0x3fb504f3, v87
	v_and_b32_e32 v87, 0xffff0000, v139
	v_fmac_f32_e32 v89, 0x3fb504f3, v87
	v_cvt_pk_bf16_f32 v87, v88, v89
	v_lshlrev_b32_e32 v88, 16, v140
	v_fmac_f32_e32 v82, 0x3fb504f3, v88
	v_and_b32_e32 v88, 0xffff0000, v140
	v_fmac_f32_e32 v83, 0x3fb504f3, v88
	v_cvt_pk_bf16_f32 v88, v82, v83
	v_lshlrev_b32_e32 v82, 16, v141
	v_fmac_f32_e32 v84, 0x3fb504f3, v82
	v_and_b32_e32 v82, 0xffff0000, v141
	v_fmac_f32_e32 v85, 0x3fb504f3, v82
	s_waitcnt vmcnt(0) lgkmcnt(0)
; __device__ __forceinline__ float bflo_(unsigned w) { return __uint_as_float(w << 16); }
; __device__ __forceinline__ float bfhi_(unsigned w) { return __uint_as_float(w & 0xffff0000u); }
; __device__ __forceinline__ unsigned cvt_pk_bf16(float lo, float hi) { unsigned r; asm volatile("v_cvt_pk_bf16_f32 %0, %1, %2" : "=v"(r) : "v"(lo), "v"(hi)); return r; }
;     __device__ __forceinline__ void operator()(const f32x4 (&acc)[2][2][4][2], const Unit& u, int wr, int wc, int fr, int fq) const {
;     ...
;             for (int m = 0; m < 4; ++m)
; #pragma unroll
;                 for (int bj = 0; bj < 2; ++bj) { const f32x4 v0 = acc[ai][bj][m][0], v1 = acc[ai][bj][m][1]; const u32x4 hh = h[m][bj];
;                     u32x4 w;
;                     w.x = cvt_pk_bf16(bflo_(hh.x) * alpha + v0[0], bfhi_(hh.x) * alpha + v0[1]); w.y = cvt_pk_bf16(bflo_(hh.y) * alpha + v0[2], bfhi_(hh.y) * alpha + v0[3]);
;                     w.z = cvt_pk_bf16(bflo_(hh.z) * alpha + v1[0], bfhi_(hh.z) * alpha + v1[1]); w.w = cvt_pk_bf16(bflo_(hh.w) * alpha + v1[2], bfhi_(hh.w) * alpha + v1[3]);
;                     *(u32x4*)(p + m * step + bj * HALF * 2) = w; }
;             p += 8 * step;
	v_lshlrev_b32_e32 v82, 16, v134
	v_fmac_f32_e32 v78, 0x3fb504f3, v82
	v_and_b32_e32 v82, 0xffff0000, v134
	v_fmac_f32_e32 v79, 0x3fb504f3, v82
	v_cvt_pk_bf16_f32 v89, v84, v85
	flat_store_dwordx4 v[158:159], v[86:89] offset:256
	v_cvt_pk_bf16_f32 v78, v78, v79
	v_lshlrev_b32_e32 v79, 16, v135
	v_fmac_f32_e32 v80, 0x3fb504f3, v79
	v_and_b32_e32 v79, 0xffff0000, v135
	v_fmac_f32_e32 v81, 0x3fb504f3, v79
	v_cvt_pk_bf16_f32 v79, v80, v81
	v_lshlrev_b32_e32 v80, 16, v136
	v_fmac_f32_e32 v74, 0x3fb504f3, v80
	v_and_b32_e32 v80, 0xffff0000, v136
	v_fmac_f32_e32 v75, 0x3fb504f3, v80
	v_cvt_pk_bf16_f32 v80, v74, v75
	v_lshlrev_b32_e32 v74, 16, v137
	v_fmac_f32_e32 v76, 0x3fb504f3, v74
	v_and_b32_e32 v74, 0xffff0000, v137
	v_fmac_f32_e32 v77, 0x3fb504f3, v74
	v_lshlrev_b32_e32 v74, 16, v130
	v_fmac_f32_e32 v70, 0x3fb504f3, v74
	v_and_b32_e32 v74, 0xffff0000, v130
	v_fmac_f32_e32 v71, 0x3fb504f3, v74
	v_cvt_pk_bf16_f32 v81, v76, v77
	flat_store_dwordx4 v[156:157], v[78:81]
	v_cvt_pk_bf16_f32 v70, v70, v71
	v_lshlrev_b32_e32 v71, 16, v131
	v_fmac_f32_e32 v72, 0x3fb504f3, v71
	v_and_b32_e32 v71, 0xffff0000, v131
	v_fmac_f32_e32 v73, 0x3fb504f3, v71
	v_cvt_pk_bf16_f32 v71, v72, v73
	v_lshlrev_b32_e32 v72, 16, v132
	v_fmac_f32_e32 v66, 0x3fb504f3, v72
	v_and_b32_e32 v72, 0xffff0000, v132
	v_fmac_f32_e32 v67, 0x3fb504f3, v72
	v_cvt_pk_bf16_f32 v72, v66, v67
	v_lshlrev_b32_e32 v66, 16, v133
	v_fmac_f32_e32 v68, 0x3fb504f3, v66
	v_and_b32_e32 v66, 0xffff0000, v133
	v_lshl_add_u64 v[100:101], v[154:155], 0, s[24:25]
	v_fmac_f32_e32 v69, 0x3fb504f3, v66
	v_cvt_pk_bf16_f32 v73, v68, v69
	flat_store_dwordx4 v[156:157], v[70:73] offset:256
	flat_load_dwordx4 v[72:75], v[100:101]
	flat_load_dwordx4 v[76:79], v[100:101] offset:256
	v_add_co_u32_e32 v102, vcc, s87, v100
	s_waitcnt vmcnt(0) lgkmcnt(0)
	v_lshlrev_b32_e32 v106, 16, v72
	v_addc_co_u32_e32 v103, vcc, 0, v101, vcc
	flat_load_dwordx4 v[80:83], v[102:103]
	flat_load_dwordx4 v[84:87], v[102:103] offset:256
	v_add_co_u32_e32 v104, vcc, s91, v100
	v_and_b32_e32 v72, 0xffff0000, v72
	s_nop 0
	v_addc_co_u32_e32 v105, vcc, 0, v101, vcc
	flat_load_dwordx4 v[88:91], v[104:105]
	flat_load_dwordx4 v[92:95], v[104:105] offset:256
	v_add_co_u32_e32 v70, vcc, s86, v100
	v_fmac_f32_e32 v62, 0x3fb504f3, v106
	s_nop 0
	v_addc_co_u32_e32 v71, vcc, 0, v101, vcc
	flat_load_dwordx4 v[96:99], v[70:71]
	flat_load_dwordx4 v[66:69], v[70:71] offset:256
	v_fmac_f32_e32 v63, 0x3fb504f3, v72
	v_cvt_pk_bf16_f32 v62, v62, v63
	v_lshlrev_b32_e32 v63, 16, v73
	v_fmac_f32_e32 v64, 0x3fb504f3, v63
	v_and_b32_e32 v63, 0xffff0000, v73
	v_fmac_f32_e32 v65, 0x3fb504f3, v63
	v_cvt_pk_bf16_f32 v63, v64, v65
	v_lshlrev_b32_e32 v64, 16, v74
	v_fmac_f32_e32 v58, 0x3fb504f3, v64
	v_and_b32_e32 v64, 0xffff0000, v74
	v_fmac_f32_e32 v59, 0x3fb504f3, v64
	v_cvt_pk_bf16_f32 v64, v58, v59
	v_lshlrev_b32_e32 v58, 16, v75
	v_fmac_f32_e32 v60, 0x3fb504f3, v58
	v_and_b32_e32 v58, 0xffff0000, v75
	v_fmac_f32_e32 v61, 0x3fb504f3, v58
	v_lshlrev_b32_e32 v58, 16, v76
	v_fmac_f32_e32 v54, 0x3fb504f3, v58
	v_and_b32_e32 v58, 0xffff0000, v76
	v_fmac_f32_e32 v55, 0x3fb504f3, v58
	v_cvt_pk_bf16_f32 v65, v60, v61
	flat_store_dwordx4 v[100:101], v[62:65]
	v_cvt_pk_bf16_f32 v54, v54, v55
	v_lshlrev_b32_e32 v55, 16, v77
	v_fmac_f32_e32 v56, 0x3fb504f3, v55
	v_and_b32_e32 v55, 0xffff0000, v77
	v_fmac_f32_e32 v57, 0x3fb504f3, v55
	v_cvt_pk_bf16_f32 v55, v56, v57
	v_lshlrev_b32_e32 v56, 16, v78
	v_fmac_f32_e32 v50, 0x3fb504f3, v56
	v_and_b32_e32 v56, 0xffff0000, v78
	v_fmac_f32_e32 v51, 0x3fb504f3, v56
	v_cvt_pk_bf16_f32 v56, v50, v51
	v_lshlrev_b32_e32 v50, 16, v79
	v_fmac_f32_e32 v52, 0x3fb504f3, v50
	v_and_b32_e32 v50, 0xffff0000, v79
	v_fmac_f32_e32 v53, 0x3fb504f3, v50
	v_cvt_pk_bf16_f32 v57, v52, v53
	flat_store_dwordx4 v[100:101], v[54:57] offset:256
	s_waitcnt vmcnt(0) lgkmcnt(0)
; __device__ __forceinline__ float bflo_(unsigned w) { return __uint_as_float(w << 16); }
; __device__ __forceinline__ float bfhi_(unsigned w) { return __uint_as_float(w & 0xffff0000u); }
; __device__ __forceinline__ unsigned cvt_pk_bf16(float lo, float hi) { unsigned r; asm volatile("v_cvt_pk_bf16_f32 %0, %1, %2" : "=v"(r) : "v"(lo), "v"(hi)); return r; }
; #define PG8_BAR __builtin_amdgcn_s_barrier()
; template <class Epi, class Sched>
; __device__ __forceinline__ void gemm_phase(LAS unsigned char* lds, const Gemm g, const Sched& S, const Epi& E) {
;     ...
;         cur = nxt; cA = nA; cB = nB; ++ui;
;         if (wr == 1) PG8_BAR;
;     __device__ __forceinline__ void operator()(const f32x4 (&acc)[2][2][4][2], const Unit& u, int wr, int wc, int fr, int fq) const {
;     ...
;             for (int m = 0; m < 4; ++m)
; #pragma unroll
;                 for (int bj = 0; bj < 2; ++bj) { const f32x4 v0 = acc[ai][bj][m][0], v1 = acc[ai][bj][m][1]; const u32x4 hh = h[m][bj];
;                     u32x4 w;
;                     w.x = cvt_pk_bf16(bflo_(hh.x) * alpha + v0[0], bfhi_(hh.x) * alpha + v0[1]); w.y = cvt_pk_bf16(bflo_(hh.y) * alpha + v0[2], bfhi_(hh.y) * alpha + v0[3]);
;                     w.z = cvt_pk_bf16(bflo_(hh.z) * alpha + v1[0], bfhi_(hh.z) * alpha + v1[1]); w.w = cvt_pk_bf16(bflo_(hh.w) * alpha + v1[2], bfhi_(hh.w) * alpha + v1[3]);
;                     *(u32x4*)(p + m * step + bj * HALF * 2) = w; }
;             p += 8 * step;
	v_lshlrev_b32_e32 v50, 16, v80
	v_fmac_f32_e32 v46, 0x3fb504f3, v50
	v_and_b32_e32 v50, 0xffff0000, v80
	v_fmac_f32_e32 v47, 0x3fb504f3, v50
	v_cvt_pk_bf16_f32 v46, v46, v47
	v_lshlrev_b32_e32 v47, 16, v81
	v_fmac_f32_e32 v48, 0x3fb504f3, v47
	v_and_b32_e32 v47, 0xffff0000, v81
	v_fmac_f32_e32 v49, 0x3fb504f3, v47
	v_cvt_pk_bf16_f32 v47, v48, v49
	v_lshlrev_b32_e32 v48, 16, v82
	v_fmac_f32_e32 v42, 0x3fb504f3, v48
	v_and_b32_e32 v48, 0xffff0000, v82
	v_fmac_f32_e32 v43, 0x3fb504f3, v48
	v_cvt_pk_bf16_f32 v48, v42, v43
	v_lshlrev_b32_e32 v42, 16, v83
	v_fmac_f32_e32 v44, 0x3fb504f3, v42
	v_and_b32_e32 v42, 0xffff0000, v83
	v_fmac_f32_e32 v45, 0x3fb504f3, v42
	v_lshlrev_b32_e32 v42, 16, v84
	v_fmac_f32_e32 v38, 0x3fb504f3, v42
	v_and_b32_e32 v42, 0xffff0000, v84
	v_fmac_f32_e32 v39, 0x3fb504f3, v42
	v_cvt_pk_bf16_f32 v49, v44, v45
	flat_store_dwordx4 v[102:103], v[46:49]
	v_cvt_pk_bf16_f32 v38, v38, v39
	v_lshlrev_b32_e32 v39, 16, v85
	v_fmac_f32_e32 v40, 0x3fb504f3, v39
	v_and_b32_e32 v39, 0xffff0000, v85
	v_fmac_f32_e32 v41, 0x3fb504f3, v39
	v_cvt_pk_bf16_f32 v39, v40, v41
	v_lshlrev_b32_e32 v40, 16, v86
	v_fmac_f32_e32 v34, 0x3fb504f3, v40
	v_and_b32_e32 v40, 0xffff0000, v86
	v_fmac_f32_e32 v35, 0x3fb504f3, v40
	v_cvt_pk_bf16_f32 v40, v34, v35
	v_lshlrev_b32_e32 v34, 16, v87
	v_fmac_f32_e32 v36, 0x3fb504f3, v34
	v_and_b32_e32 v34, 0xffff0000, v87
	v_fmac_f32_e32 v37, 0x3fb504f3, v34
	v_lshlrev_b32_e32 v34, 16, v88
	v_fmac_f32_e32 v30, 0x3fb504f3, v34
	v_and_b32_e32 v34, 0xffff0000, v88
	v_fmac_f32_e32 v31, 0x3fb504f3, v34
	v_cvt_pk_bf16_f32 v41, v36, v37
	flat_store_dwordx4 v[102:103], v[38:41] offset:256
	v_cvt_pk_bf16_f32 v30, v30, v31
	v_lshlrev_b32_e32 v31, 16, v89
	v_fmac_f32_e32 v32, 0x3fb504f3, v31
	v_and_b32_e32 v31, 0xffff0000, v89
	v_fmac_f32_e32 v33, 0x3fb504f3, v31
	v_cvt_pk_bf16_f32 v31, v32, v33
	v_lshlrev_b32_e32 v32, 16, v90
	v_fmac_f32_e32 v26, 0x3fb504f3, v32
	v_and_b32_e32 v32, 0xffff0000, v90
	v_fmac_f32_e32 v27, 0x3fb504f3, v32
	v_cvt_pk_bf16_f32 v32, v26, v27
	v_lshlrev_b32_e32 v26, 16, v91
	v_fmac_f32_e32 v28, 0x3fb504f3, v26
	v_and_b32_e32 v26, 0xffff0000, v91
	v_fmac_f32_e32 v29, 0x3fb504f3, v26
	v_lshlrev_b32_e32 v26, 16, v92
	v_fmac_f32_e32 v22, 0x3fb504f3, v26
	v_and_b32_e32 v26, 0xffff0000, v92
	v_fmac_f32_e32 v23, 0x3fb504f3, v26
	v_cvt_pk_bf16_f32 v33, v28, v29
	flat_store_dwordx4 v[104:105], v[30:33]
	v_cvt_pk_bf16_f32 v22, v22, v23
	v_lshlrev_b32_e32 v23, 16, v93
	v_fmac_f32_e32 v24, 0x3fb504f3, v23
	v_and_b32_e32 v23, 0xffff0000, v93
	v_fmac_f32_e32 v25, 0x3fb504f3, v23
	v_cvt_pk_bf16_f32 v23, v24, v25
	v_lshlrev_b32_e32 v24, 16, v94
	v_fmac_f32_e32 v18, 0x3fb504f3, v24
	v_and_b32_e32 v24, 0xffff0000, v94
	v_fmac_f32_e32 v19, 0x3fb504f3, v24
	v_cvt_pk_bf16_f32 v24, v18, v19
	v_lshlrev_b32_e32 v18, 16, v95
	v_fmac_f32_e32 v20, 0x3fb504f3, v18
	v_and_b32_e32 v18, 0xffff0000, v95
	v_fmac_f32_e32 v21, 0x3fb504f3, v18
	v_lshlrev_b32_e32 v18, 16, v96
	v_fmac_f32_e32 v14, 0x3fb504f3, v18
	v_and_b32_e32 v18, 0xffff0000, v96
	v_fmac_f32_e32 v15, 0x3fb504f3, v18
	v_cvt_pk_bf16_f32 v25, v20, v21
	flat_store_dwordx4 v[104:105], v[22:25] offset:256
	v_cvt_pk_bf16_f32 v14, v14, v15
	v_lshlrev_b32_e32 v15, 16, v97
	v_fmac_f32_e32 v16, 0x3fb504f3, v15
	v_and_b32_e32 v15, 0xffff0000, v97
	v_fmac_f32_e32 v17, 0x3fb504f3, v15
	v_cvt_pk_bf16_f32 v15, v16, v17
	v_lshlrev_b32_e32 v16, 16, v98
	v_fmac_f32_e32 v10, 0x3fb504f3, v16
	v_and_b32_e32 v16, 0xffff0000, v98
	v_fmac_f32_e32 v11, 0x3fb504f3, v16
	v_cvt_pk_bf16_f32 v16, v10, v11
	v_lshlrev_b32_e32 v10, 16, v99
	v_fmac_f32_e32 v12, 0x3fb504f3, v10
	v_and_b32_e32 v10, 0xffff0000, v99
	v_fmac_f32_e32 v13, 0x3fb504f3, v10
	v_lshlrev_b32_e32 v10, 16, v66
	v_fmac_f32_e32 v6, 0x3fb504f3, v10
	v_and_b32_e32 v10, 0xffff0000, v66
	v_fmac_f32_e32 v7, 0x3fb504f3, v10
	v_cvt_pk_bf16_f32 v17, v12, v13
	flat_store_dwordx4 v[70:71], v[14:17]
	v_cvt_pk_bf16_f32 v6, v6, v7
	v_lshlrev_b32_e32 v7, 16, v67
	v_fmac_f32_e32 v8, 0x3fb504f3, v7
	v_and_b32_e32 v7, 0xffff0000, v67
	v_fmac_f32_e32 v9, 0x3fb504f3, v7
	v_cvt_pk_bf16_f32 v7, v8, v9
	v_lshlrev_b32_e32 v8, 16, v68
	v_fmac_f32_e32 v2, 0x3fb504f3, v8
	v_and_b32_e32 v8, 0xffff0000, v68
	v_fmac_f32_e32 v3, 0x3fb504f3, v8
	v_cvt_pk_bf16_f32 v8, v2, v3
	v_lshlrev_b32_e32 v2, 16, v69
	v_fmac_f32_e32 v4, 0x3fb504f3, v2
	v_and_b32_e32 v2, 0xffff0000, v69
	v_fmac_f32_e32 v5, 0x3fb504f3, v2
	v_cvt_pk_bf16_f32 v9, v4, v5
	flat_store_dwordx4 v[70:71], v[6:9] offset:256
	s_cbranch_scc1 .LBB0_445
	s_andn2_b64 vcc, exec, s[26:27]
	s_cbranch_vccnz .LBB0_444
	s_barrier
	s_branch .LBB0_444
